# GEMM0 rounds reordered so the gate tile is last; split-phase GEMM0->attention boundary: waves signal when the q/k/V^T tiles are stored, the boundary waits only for that, gate readiness is checked at t
# speedup vs baseline: 1.0006x; 1.0006x over previous
;     __host__ __device__ bool next(int i, Unit& u) const {
;         const long L = (long)i * G + c; if (L >= nwg) return false;
;         int wgid = (int)L; { const int q = nwg / NXCD, r = nwg % NXCD, xcd = wgid % NXCD, off = wgid / NXCD; wgid = (xcd < r ? xcd * (q + 1) : r * (q + 1) + (xcd - r) * q) + off; }
;         const int nig = WGM * nN, gid = wgid / nig, fm = gid * WGM, gsz = (nM - fm) < WGM ? (nM - fm) : WGM;
;         u.pm = fm + ((wgid % nig) % gsz); u.pn = (wgid % nig) / gsz; return true;
; template <class Epi, class Sched, bool ALIGN_EPI = false, bool SP2 = false>
; __device__ __forceinline__ void gemm_phase(PG8_LAS unsigned char* lds, const Gemm g, const Sched& S, const Epi& E) {
;     ...
;         const bool has_next = S.next(ui + 1, nxt);
.LBB0_109:
	s_add_i32 s38, s38, 1
	s_cmp_eq_u32 s38, 2
	s_cselect_b32 s9, 3, s38
	s_cmp_eq_u32 s38, 3
	s_cselect_b32 s9, 2, s9
	v_readlane_b32 s6, v254, 7
	v_readlane_b32 s8, v254, 6
	s_mul_i32 s6, s9, s6
	s_mul_hi_u32 s7, s9, s8
	s_add_i32 s7, s7, s6
	s_mul_i32 s6, s9, s8
	s_add_u32 s8, s6, s84
	s_addc_u32 s9, s7, s90
	v_mov_b64_e32 v[0:1], 0x400
	v_cmp_gt_i64_e32 vcc, s[8:9], v[246:247]
	v_cmp_lt_i64_e64 s[6:7], s[8:9], v[0:1]
	s_cbranch_vccnz .LBB0_115
	s_ashr_i32 s9, s8, 31
	s_lshr_b32 s9, s9, 29
	s_add_i32 s11, s8, s9
	s_and_b32 s9, s11, -8
	s_sub_i32 s12, s8, s9
	s_cmp_gt_i32 s12, -1
	s_mov_b64 s[8:9], -1
	s_cbranch_scc0 .LBB0_112
	s_lshl_b32 s13, s12, 7
	s_mov_b64 s[8:9], 0

;     __device__ __forceinline__ void operator()(const f32x4 (&acc)[2][2][4][2], const Unit& u, int wr, int wc, int fr, int fq) const {
;     ...
;             for (int m = 0; m < 4; ++m) part[ai][m] = *(const f32x4*)(rss + (size_t)(u.pm * BM + ai * HALF + wr * 64 + m * 16 + fr) * 16 + 4 * fq);
;     ...
;                     if (tn < 24) {
;                         bf16_t* dst;
;                         if (tn < 8) dst = z + (size_t)(tn >> 2) * ZS_KD + ((size_t)((b * 4 + (tn & 3)) * 2048 + s)) * 128 + cw;
;                         else if (tn < 16) dst = z + ZS_QN + (size_t)((tn - 8) >> 2) * (ZS_KN - ZS_QN) + ((size_t)((b * 8 + ((tn - 8) & 3) * 2 + (cw >> 6)) * 2048 + s)) * 64 + (cw & 63);
;                         else dst = z + ZS_GATE + (size_t)row * 1024 + (tn - 16) * 128 + cw;
;                         *(u32x4*)dst = w;
;                     } else {
;                         const unsigned ox = __shfl_xor(w.x, 1), oy = __shfl_xor(w.y, 1), oz = __shfl_xor(w.z, 1), ow = __shfl_xor(w.w, 1);
;                         const bool odd = fr & 1;
;                         const unsigned a0 = odd ? oz : w.x, a1 = odd ? ow : w.y;
;                         const unsigned b0 = odd ? w.z : ox, b1 = odd ? w.w : oy;
;                         const unsigned p0 = (a0 & 0xffffu) | (b0 << 16), p1 = (a0 >> 16) | (b0 & 0xffff0000u);
;                         const unsigned p2 = (a1 & 0xffffu) | (b1 << 16), p3 = (a1 >> 16) | (b1 & 0xffff0000u);
;                         const int ch0 = cw + (odd ? 4 : 0), se = s & ~1;
;                         bf16_t* dst;
;                         if (tn < 28) dst = vT + VS_VD + ((size_t)(((b * 4 + (tn - 24)) * 32 + (se >> 6)) * 128 + ch0)) * 64 + (se & 63);
;                         else dst = vT + VS_VN + ((size_t)(((b * 8 + (tn - 28) * 2 + (ch0 >> 6)) * 32 + (se >> 6)) * 64 + (ch0 & 63))) * 64 + (se & 63);
;                         *(unsigned*)(dst) = p0; *(unsigned*)(dst + 64) = p1; *(unsigned*)(dst + 128) = p2; *(unsigned*)(dst + 192) = p3;
.LBB0_119:
	s_lshl_b32 s33, s10, 8
	v_add_u32_e32 v128, s33, v167
	v_ashrrev_i32_e32 v129, 31, v128
	v_lshlrev_b64 v[130:131], 6, v[128:129]
	v_lshl_add_u64 v[130:131], v[168:169], 0, v[130:131]
	global_load_dwordx4 v[174:177], v[130:131], off
	v_or_b32_e32 v130, 16, v128
	v_ashrrev_i32_e32 v131, 31, v130
	v_lshlrev_b64 v[130:131], 6, v[130:131]
	v_lshl_add_u64 v[130:131], v[168:169], 0, v[130:131]
	global_load_dwordx4 v[178:181], v[130:131], off
	v_or_b32_e32 v130, 32, v128
	v_ashrrev_i32_e32 v131, 31, v130
	v_lshlrev_b64 v[130:131], 6, v[130:131]
	v_lshl_add_u64 v[130:131], v[168:169], 0, v[130:131]
	global_load_dwordx4 v[188:191], v[130:131], off
	v_or_b32_e32 v130, 48, v128
	v_ashrrev_i32_e32 v131, 31, v130
	v_lshlrev_b64 v[130:131], 6, v[130:131]
	v_lshl_add_u64 v[130:131], v[168:169], 0, v[130:131]
	global_load_dwordx4 v[192:195], v[130:131], off
	v_add_u32_e32 v130, 0x80, v128
	v_ashrrev_i32_e32 v131, 31, v130
	v_lshlrev_b64 v[130:131], 6, v[130:131]
	v_lshl_add_u64 v[130:131], v[168:169], 0, v[130:131]
	global_load_dwordx4 v[136:139], v[130:131], off
	v_add_u32_e32 v130, 0x90, v128
	v_ashrrev_i32_e32 v131, 31, v130
	v_lshlrev_b64 v[130:131], 6, v[130:131]
	v_lshl_add_u64 v[130:131], v[168:169], 0, v[130:131]
	global_load_dwordx4 v[140:143], v[130:131], off
	v_add_u32_e32 v130, 0xa0, v128
	v_add_u32_e32 v128, 0xb0, v128
	v_ashrrev_i32_e32 v131, 31, v130
	v_ashrrev_i32_e32 v129, 31, v128
	v_lshlrev_b64 v[130:131], 6, v[130:131]
	v_lshlrev_b64 v[128:129], 6, v[128:129]
	v_lshl_add_u64 v[130:131], v[168:169], 0, v[130:131]
	v_lshl_add_u64 v[128:129], v[168:169], 0, v[128:129]
	global_load_dwordx4 v[132:135], v[130:131], off
	v_and_b32_e32 v156, 64, v240
	global_load_dwordx4 v[128:131], v[128:129], off
	v_xor_b32_e32 v152, 16, v240
	v_add_u32_e32 v186, 64, v156
	v_cmp_lt_i32_e32 vcc, v152, v186
	v_xor_b32_e32 v156, 32, v240
	s_mov_b32 s0, 0x3a800000
	v_cndmask_b32_e32 v152, v240, v152, vcc
	v_lshlrev_b32_e32 v152, 2, v152
	v_cmp_lt_i32_e32 vcc, v156, v186
	s_add_i32 s33, s33, s35
	s_ashr_i32 s44, s33, 11
	v_cndmask_b32_e32 v156, v240, v156, vcc
	v_lshlrev_b32_e32 v156, 2, v156
	s_lshl_b32 s19, s41, 1
	s_mov_b64 s[2:3], -1
	s_waitcnt vmcnt(0)
	s_cmp_lg_u32 s38, 4
	s_cbranch_scc1 .Lsp_noarr
	s_cmp_eq_u32 s99, 0
	s_cbranch_scc1 .Lsp_noarr
	v_readlane_b32 s8, v254, 2
	s_lshl_b32 s8, s8, 8
	s_mov_b64 s[100:101], exec
	s_mov_b64 exec, 1
	v_mov_b32_e32 v157, s8
	v_mov_b32_e32 v158, 1
	global_atomic_add v157, v158, s[82:83] offset:1184
	s_mov_b64 exec, s[100:101]
.Lsp_noarr:
	v_mov_b32_e32 v196, v175
	v_mov_b32_e32 v197, v176
	v_mov_b32_e32 v175, v177
	v_pk_add_f32 v[174:175], v[196:197], v[174:175]
	v_mov_b32_e32 v176, v179
	v_mov_b32_e32 v177, v180
	v_mov_b32_e32 v179, v181
	v_pk_add_f32 v[176:177], v[176:177], v[178:179]
	v_mov_b32_e32 v179, v174
	v_mov_b32_e32 v178, v176
	v_mov_b32_e32 v174, v177
	v_pk_add_f32 v[174:175], v[178:179], v[174:175]
	ds_bpermute_b32 v177, v152, v175
	ds_bpermute_b32 v176, v152, v174
	s_waitcnt lgkmcnt(0)
	v_pk_add_f32 v[174:175], v[174:175], v[176:177]
	ds_bpermute_b32 v177, v156, v175
	ds_bpermute_b32 v176, v156, v174
	s_waitcnt lgkmcnt(0)
	v_pk_add_f32 v[174:175], v[174:175], v[176:177]
	s_nop 0
	v_pk_fma_f32 v[178:179], v[174:175], s[0:1], v[236:237] op_sel_hi:[1,0,0]
	v_mov_b32_e32 v174, v189
	v_mov_b32_e32 v175, v190
	v_mov_b32_e32 v189, v191
	v_mov_b32_e32 v176, v193
	v_mov_b32_e32 v177, v194
	v_mov_b32_e32 v193, v195
	v_pk_add_f32 v[174:175], v[174:175], v[188:189]
	v_pk_add_f32 v[176:177], v[176:177], v[192:193]
	v_mov_b32_e32 v189, v174
	v_mov_b32_e32 v188, v176
	v_mov_b32_e32 v174, v177
	v_pk_add_f32 v[174:175], v[188:189], v[174:175]
	v_mov_b32_e32 v188, v137
	v_mov_b32_e32 v189, v138
	v_mov_b32_e32 v137, v139
	v_mov_b32_e32 v138, v141
	v_mov_b32_e32 v139, v142
	v_mov_b32_e32 v141, v143
	v_pk_add_f32 v[136:137], v[188:189], v[136:137]
	v_pk_add_f32 v[138:139], v[138:139], v[140:141]
	v_mov_b32_e32 v141, v136
	v_mov_b32_e32 v140, v138
	v_mov_b32_e32 v136, v139
	v_pk_add_f32 v[136:137], v[140:141], v[136:137]
	v_mov_b32_e32 v140, v133
	v_mov_b32_e32 v141, v134
	v_mov_b32_e32 v133, v135
	v_mov_b32_e32 v134, v129
	v_mov_b32_e32 v135, v130
	v_mov_b32_e32 v129, v131
	v_pk_add_f32 v[132:133], v[140:141], v[132:133]
	v_pk_add_f32 v[128:129], v[134:135], v[128:129]
	v_mov_b32_e32 v131, v132
	v_mov_b32_e32 v130, v128
	v_mov_b32_e32 v132, v129
	v_pk_add_f32 v[128:129], v[130:131], v[132:133]
	ds_bpermute_b32 v177, v152, v175
	ds_bpermute_b32 v176, v152, v174
	ds_bpermute_b32 v139, v152, v137
	ds_bpermute_b32 v138, v152, v136
	ds_bpermute_b32 v131, v152, v129
	ds_bpermute_b32 v130, v152, v128
	v_mul_f32_e32 v157, 0x4b800000, v179
	v_cmp_gt_f32_e32 vcc, s96, v179
	s_and_b32 s0, s33, 0x7c0
	s_waitcnt lgkmcnt(4)
	v_pk_add_f32 v[174:175], v[174:175], v[176:177]
	v_cndmask_b32_e32 v157, v179, v157, vcc
	v_rsq_f32_e32 v157, v157
	s_waitcnt lgkmcnt(2)
	v_pk_add_f32 v[136:137], v[136:137], v[138:139]
	s_waitcnt lgkmcnt(0)
	v_pk_add_f32 v[128:129], v[128:129], v[130:131]
	v_or_b32_e32 v135, s0, v184
	s_lshl_b32 s0, s44, 7
	s_bfe_u32 s1, s33, 0x50006
	ds_bpermute_b32 v177, v156, v175
	ds_bpermute_b32 v176, v156, v174
	ds_bpermute_b32 v139, v156, v137
	ds_bpermute_b32 v138, v156, v136
	ds_bpermute_b32 v131, v156, v129
	ds_bpermute_b32 v130, v156, v128
	s_or_b32 s43, s0, s1
	v_mul_f32_e32 v158, 0x45800000, v157
	s_add_i32 s43, s43, 0x1fffd00
	v_cndmask_b32_e32 v180, v157, v158, vcc
	s_cmp_gt_i32 s41, 11
	v_pk_mul_f32 v[126:127], v[126:127], v[180:181] op_sel_hi:[1,0]
	v_pk_mul_f32 v[124:125], v[124:125], v[180:181] op_sel_hi:[1,0]
	v_pk_mul_f32 v[132:133], v[122:123], v[180:181] op_sel_hi:[1,0]
	v_pk_mul_f32 v[122:123], v[120:121], v[180:181] op_sel_hi:[1,0]
	s_cselect_b64 s[0:1], -1, 0
	v_xor_b32_e32 v134, 1, v240
	v_cmp_gt_f32_e64 s[8:9], s96, v178
	v_cvt_pk_bf16_f32 v120, v124, v125
	v_cvt_pk_bf16_f32 v121, v126, v127
	v_cvt_pk_bf16_f32 v122, v122, v123
	v_cvt_pk_bf16_f32 v123, v132, v133
	s_and_b64 vcc, exec, s[0:1]
	v_cmp_lt_i32_e64 s[10:11], v134, v186
	s_cbranch_vccz .LBB0_125
	s_nop 0
	v_cndmask_b32_e64 v124, v240, v134, s[10:11]
	v_lshlrev_b32_e32 v124, 2, v124
	ds_bpermute_b32 v125, v124, v120
	ds_bpermute_b32 v126, v124, v121
	ds_bpermute_b32 v127, v124, v122
	ds_bpermute_b32 v132, v124, v123
	s_lshl_b32 s12, s41, 13
	s_cmp_gt_u32 s19, 27
	s_cbranch_scc0 .LBB0_122
	s_lshl_b32 s2, s44, 14
	s_add_i32 s3, s12, s40
	s_add_i32 s3, s3, s2
	v_or_b32_e32 v124, s3, v135
	s_mov_b64 s[2:3], s[68:69]
	s_cbranch_execz .LBB0_123
	s_branch .LBB0_124

; __device__ __forceinline__ unsigned xb_ld(unsigned* p)              { return __hip_atomic_load(p, __ATOMIC_RELAXED, __HIP_MEMORY_SCOPE_AGENT); }
; __device__ __forceinline__ unsigned xb_add(unsigned* p, unsigned v) { return __hip_atomic_fetch_add(p, v, __ATOMIC_RELAXED, __HIP_MEMORY_SCOPE_AGENT); }
; #define XB_SPIN(cond, bar) do { unsigned _sp = 0; while (cond) { __builtin_amdgcn_s_sleep(1); \
;     if ((++_sp & 255u) == 0u) { if (xb_ld(&(bar)[XB_TMO])) break; if (_sp > XB_SPIN_CAP) { atomicAdd(&(bar)[XB_TMO], 1u); break; } } } } while (0)
; __device__ __forceinline__ void xcd_barrier(const XcdBarrier& b) {
;     ...
;         const unsigned old = xb_add(&bar[XB_XSUB(bx)], 1u);
;         const unsigned gen = old / nloc;
;         if (old + 1u == (gen + 1u) * nloc) {
;             __builtin_amdgcn_fence(__ATOMIC_RELEASE, "agent");
;             asm volatile("s_waitcnt vmcnt(0)" ::: "memory");
;             const unsigned og = xb_add(&bar[XB_TOP], 1u);
;             const unsigned tg = og / nx;
;             if (og + 1u == (tg + 1u) * nx) xb_add(&bar[XB_TOPGEN], 1u);
;             else XB_SPIN(xb_ld(&bar[XB_TOPGEN]) == tg, bar);
;             __builtin_amdgcn_fence(__ATOMIC_ACQUIRE, "agent");
;             xb_add(&bar[XB_XGEN(bx)], 1u);
;             asm volatile("s_waitcnt vmcnt(0)" ::: "memory");
;         } else {
;             XB_SPIN(xb_ld(&bar[XB_XGEN(bx)]) == gen, bar);
.Lwc_pskip_2:
	s_cmp_eq_u32 s99, 0
	s_cbranch_scc1 .Lxb_full_1
	v_readlane_b32 s2, v254, 2
	v_mov_b32_e32 v1, 1
	s_lshl_b32 s2, s2, 8
	s_mov_b32 s98, 0
	v_mov_b32_e32 v0, s2
	buffer_inv sc1
	global_atomic_add v0, v1, s[82:83] offset:1216
	v_readlane_b32 s3, v254, 58
	s_add_i32 s3, s3, 1
	s_lshl_b32 s3, s3, 8
.Lxb_spin_1:
	global_load_dword v2, v0, s[82:83] offset:1184 sc1
	s_add_u32 s98, s98, 1
	s_waitcnt vmcnt(0)
	v_readfirstlane_b32 s2, v2
	s_cmp_ge_u32 s2, s3
	s_cbranch_scc1 .Lxb_done_1
	s_cmp_lt_u32 s98, 0x100000
	s_cbranch_scc0 .Lxb_done_1
	s_sleep 1
	s_branch .Lxb_spin_1

; __device__ void na_super(char* lds, const Params& p, int layer, int su) {
;     ...
;     u32x2 gwv[4][4];
; #pragma unroll
;     for (int n = 0; n < 4; ++n)
; #pragma unroll
;         for (int dt = 0; dt < 4; ++dt) gwv[n][dt] = *(const u32x2*)(p.z + ZS_GATE + ((size_t)b * SEQ + rq * 64 + 16 * n + fr) * 1024 + 512 + h * 64 + 16 * dt + 4 * fq);
.LBB0_464:
	s_cmp_eq_u32 s99, 0
	s_cbranch_scc1 .Lsp_nt_ok
	v_readlane_b32 s2, v254, 2
	s_lshl_b32 s2, s2, 8
	v_mov_b32_e32 v60, s2
	v_readlane_b32 s3, v254, 58
	s_add_i32 s3, s3, 1
	s_lshl_b32 s3, s3, 5
	s_mov_b32 s4, 0
.Lsp_nt_spin:
	global_load_dword v61, v60, s[82:83] offset:1216 sc1
	s_add_u32 s4, s4, 1
	s_waitcnt vmcnt(0)
	v_readfirstlane_b32 s2, v61
	s_cmp_ge_u32 s2, s3
	s_cbranch_scc1 .Lsp_nt_ok
	s_cmp_lt_u32 s4, 0x100000
	s_cbranch_scc0 .Lsp_nt_ok
	s_sleep 1
	s_branch .Lsp_nt_spin

; __device__ void da_unit(char* lds, const Params& p, int layer, int unit) {
;     ...
;             for (int g = 0; g < 4; ++g) gwv[k * 4 + g] = *(const u32x2*)(p.z + ZS_GATE + tokq * 1024 + h * 128 + 32 * k + 8 * g + 4 * h2);
;     }
;     const float lsum = lrow + __shfl_xor(lrow, 32);
;     float* xch = (float*)lds + qg * 4096;
;     if (c == 1) {
;         const float i1 = lam / lsum;
; #pragma unroll
;         for (int k = 0; k < 4; ++k)
; #pragma unroll
;             for (int e = 0; e < 16; ++e) xch[(k * 16 + e) * 64 + lane] = O[k][e] * i1;
.LBB0_525:
	s_or_b64 exec, exec, s[4:5]
	s_ashr_i32 s0, s6, 2
	s_ashr_i32 s1, s0, 31
	s_ashr_i32 s2, s7, 31
	s_lshl_b64 s[0:1], s[0:1], 11
	s_add_u32 s0, s0, s7
	s_addc_u32 s1, s1, s2
	s_cmp_eq_u32 s15, 0
	v_or_b32_e32 v64, s0, v147
	v_mov_b32_e32 v65, s1
	s_cselect_b64 s[0:1], -1, 0
	s_cmp_lg_u32 s15, 0
	s_cselect_b64 s[2:3], -1, 0
	s_and_b64 vcc, exec, s[2:3]
	v_lshlrev_b64 v[78:79], 11, v[64:65]
	v_mov_b32_e32 v253, v153
	s_lshl_b32 s70, s12, 8
	s_lshl_b32 s0, s15, 7
	s_add_i32 s70, s70, s0
	v_readlane_b32 s4, v254, 20
	v_readlane_b32 s5, v254, 21
	s_load_dword s2, s[86:87], 0xa0
	ds_bpermute_b32 v65, v244, v193
	s_nop 0
	v_lshl_add_u64 v[76:77], s[4:5], 0, v[78:79]
	v_lshl_add_u64 v[76:77], v[76:77], 0, s[70:71]
	v_lshl_add_u64 v[76:77], v[76:77], 0, v[252:253]
	s_cmp_eq_u32 s99, 0
	s_cbranch_scc1 .Lsp_dt_ok
	v_readlane_b32 s4, v254, 2
	s_lshl_b32 s4, s4, 8
	v_mov_b32_e32 v200, s4
	v_readlane_b32 s5, v254, 58
	s_add_i32 s5, s5, 1
	s_lshl_b32 s5, s5, 5
	s_mov_b32 s6, 0
.Lsp_dt_spin:
	global_load_dword v201, v200, s[82:83] offset:1216 sc1
	s_add_u32 s6, s6, 1
	s_waitcnt vmcnt(0)
	v_readfirstlane_b32 s4, v201
	s_cmp_ge_u32 s4, s5
	s_cbranch_scc1 .Lsp_dt_ok
	s_cmp_lt_u32 s6, 0x100000
	s_cbranch_scc0 .Lsp_dt_ok
	s_sleep 1
	s_branch .Lsp_dt_spin
.Lsp_dt_ok:
	global_load_dwordx2 v[200:201], v[76:77], off offset:0
	global_load_dwordx2 v[202:203], v[76:77], off offset:16
	global_load_dwordx2 v[204:205], v[76:77], off offset:32
	global_load_dwordx2 v[206:207], v[76:77], off offset:48
	global_load_dwordx2 v[208:209], v[76:77], off offset:64
	global_load_dwordx2 v[210:211], v[76:77], off offset:80
	global_load_dwordx2 v[212:213], v[76:77], off offset:96
	global_load_dwordx2 v[214:215], v[76:77], off offset:112
	v_lshl_add_u64 v[78:79], s[62:63], 0, v[78:79]
	v_lshl_add_u64 v[78:79], v[78:79], 0, s[70:71]
	v_lshl_add_u64 v[78:79], v[78:79], 0, v[252:253]
	s_lshl_b32 s4, s13, 14
	v_lshl_add_u32 v67, v184, 2, s4
	s_lshl_b32 s4, s13, 9
	s_lshl_b32 s5, s15, 8
	s_add_i32 s4, s4, s5
	s_add_i32 s4, s4, 0x10000
	v_lshl_add_u32 v68, v184, 2, s4
	s_waitcnt lgkmcnt(0)
	v_add_f32_e32 v65, v193, v65
	v_sub_f32_e32 v66, v191, v192
	v_subrev_f32_e32 v66, s2, v66
	s_cmp_eq_u32 s15, 0
	s_cselect_b64 s[0:1], -1, 0
	s_nop 0
	v_cndmask_b32_e64 v66, v66, 1.0, s[0:1]
	v_div_scale_f32 v72, s[0:1], v65, v65, v66
	v_div_scale_f32 v74, vcc, v66, v65, v66
	v_rcp_f32_e32 v73, v72
	s_nop 0
	v_fma_f32 v75, -v72, v73, 1.0
	v_fmac_f32_e32 v73, v75, v73
	v_mul_f32_e32 v75, v74, v73
	v_fma_f32 v64, -v72, v75, v74
	v_fmac_f32_e32 v75, v64, v73
	v_fma_f32 v72, -v72, v75, v74
	v_div_fmas_f32 v72, v72, v73, v75
	v_div_fixup_f32 v64, v72, v65, v66
	v_pk_mul_f32 v[48:49], v[48:49], v[64:65] op_sel_hi:[1,0]
	v_pk_mul_f32 v[50:51], v[50:51], v[64:65] op_sel_hi:[1,0]
	v_pk_mul_f32 v[52:53], v[52:53], v[64:65] op_sel_hi:[1,0]
	v_pk_mul_f32 v[54:55], v[54:55], v[64:65] op_sel_hi:[1,0]
	v_pk_mul_f32 v[56:57], v[56:57], v[64:65] op_sel_hi:[1,0]
	v_pk_mul_f32 v[58:59], v[58:59], v[64:65] op_sel_hi:[1,0]
	v_pk_mul_f32 v[60:61], v[60:61], v[64:65] op_sel_hi:[1,0]
	v_pk_mul_f32 v[62:63], v[62:63], v[64:65] op_sel_hi:[1,0]
	v_pk_mul_f32 v[32:33], v[32:33], v[64:65] op_sel_hi:[1,0]
	v_pk_mul_f32 v[34:35], v[34:35], v[64:65] op_sel_hi:[1,0]
	v_pk_mul_f32 v[36:37], v[36:37], v[64:65] op_sel_hi:[1,0]
	v_pk_mul_f32 v[38:39], v[38:39], v[64:65] op_sel_hi:[1,0]
	v_pk_mul_f32 v[40:41], v[40:41], v[64:65] op_sel_hi:[1,0]
	v_pk_mul_f32 v[42:43], v[42:43], v[64:65] op_sel_hi:[1,0]
	v_pk_mul_f32 v[44:45], v[44:45], v[64:65] op_sel_hi:[1,0]
	v_pk_mul_f32 v[46:47], v[46:47], v[64:65] op_sel_hi:[1,0]
	v_pk_mul_f32 v[16:17], v[16:17], v[64:65] op_sel_hi:[1,0]
	v_pk_mul_f32 v[18:19], v[18:19], v[64:65] op_sel_hi:[1,0]
	v_pk_mul_f32 v[20:21], v[20:21], v[64:65] op_sel_hi:[1,0]
	v_pk_mul_f32 v[22:23], v[22:23], v[64:65] op_sel_hi:[1,0]
	v_pk_mul_f32 v[24:25], v[24:25], v[64:65] op_sel_hi:[1,0]
	v_pk_mul_f32 v[26:27], v[26:27], v[64:65] op_sel_hi:[1,0]
	v_pk_mul_f32 v[28:29], v[28:29], v[64:65] op_sel_hi:[1,0]
	v_pk_mul_f32 v[30:31], v[30:31], v[64:65] op_sel_hi:[1,0]
	v_pk_mul_f32 v[0:1], v[0:1], v[64:65] op_sel_hi:[1,0]
	v_pk_mul_f32 v[2:3], v[2:3], v[64:65] op_sel_hi:[1,0]
	v_pk_mul_f32 v[4:5], v[4:5], v[64:65] op_sel_hi:[1,0]
	v_pk_mul_f32 v[6:7], v[6:7], v[64:65] op_sel_hi:[1,0]
	v_pk_mul_f32 v[8:9], v[8:9], v[64:65] op_sel_hi:[1,0]
	v_pk_mul_f32 v[10:11], v[10:11], v[64:65] op_sel_hi:[1,0]
	v_pk_mul_f32 v[12:13], v[12:13], v[64:65] op_sel_hi:[1,0]
	v_pk_mul_f32 v[14:15], v[14:15], v[64:65] op_sel_hi:[1,0]
	s_cmp_lg_u32 s15, 0
	s_cbranch_scc1 .Ldt_c1
	ds_write2st64_b32 v67, v16, v17 offset0:32 offset1:33
	ds_write2st64_b32 v67, v18, v19 offset0:34 offset1:35
	ds_write2st64_b32 v67, v20, v21 offset0:36 offset1:37
	ds_write2st64_b32 v67, v22, v23 offset0:38 offset1:39
	ds_write2st64_b32 v67, v24, v25 offset0:40 offset1:41
	ds_write2st64_b32 v67, v26, v27 offset0:42 offset1:43
	ds_write2st64_b32 v67, v28, v29 offset0:44 offset1:45
	ds_write2st64_b32 v67, v30, v31 offset0:46 offset1:47
	ds_write2st64_b32 v67, v0, v1 offset0:48 offset1:49
	ds_write2st64_b32 v67, v2, v3 offset0:50 offset1:51
	ds_write2st64_b32 v67, v4, v5 offset0:52 offset1:53
	ds_write2st64_b32 v67, v6, v7 offset0:54 offset1:55
	ds_write2st64_b32 v67, v8, v9 offset0:56 offset1:57
	ds_write2st64_b32 v67, v10, v11 offset0:58 offset1:59
	ds_write2st64_b32 v67, v12, v13 offset0:60 offset1:61
	ds_write2st64_b32 v67, v14, v15 offset0:62 offset1:63
	s_waitcnt lgkmcnt(0)
	s_barrier
; __device__ void da_unit(char* lds, const Params& p, int layer, int unit) {
;     ...
;     if (c == 0) {
;         const float i0 = 1.0f / lsum;
;         float ss = 0.f;
; #pragma unroll
;         for (int k = 0; k < 4; ++k)
; #pragma unroll
;             for (int e = 0; e < 16; ++e) { const float a = O[k][e] * i0 - xch[(k * 16 + e) * 64 + lane]; O[k][e] = a; ss += a * a; }
;         ss += __shfl_xor(ss, 32);
;         const float rstd = rsqrtf(ss * (1.0f / 128.0f) + RMS_EPS) * (1.0f - p.lam_init[layer]);
;         const float* sg = (const float*)(lds + LDS_SG_OFF);
;         __builtin_amdgcn_sched_barrier(0);
; #pragma unroll
;         for (int k = 0; k < 4; ++k)
; #pragma unroll
;             for (int g = 0; g < 4; ++g) {
;                 const int d0 = 32 * k + 8 * g + 4 * h2;
;                 const f32x4 gg = *(const f32x4*)(sg + d0);
	ds_read2st64_b32 v[80:81], v67 offset0:0 offset1:1
	ds_read2st64_b32 v[82:83], v67 offset0:2 offset1:3
	ds_read2st64_b32 v[84:85], v67 offset0:4 offset1:5
	ds_read2st64_b32 v[86:87], v67 offset0:6 offset1:7
	ds_read2st64_b32 v[88:89], v67 offset0:8 offset1:9
	ds_read2st64_b32 v[90:91], v67 offset0:10 offset1:11
	ds_read2st64_b32 v[92:93], v67 offset0:12 offset1:13
	ds_read2st64_b32 v[94:95], v67 offset0:14 offset1:15
	s_waitcnt lgkmcnt(0)
	v_pk_add_f32 v[48:49], v[48:49], v[80:81]
	v_pk_add_f32 v[50:51], v[50:51], v[82:83]
	v_pk_add_f32 v[52:53], v[52:53], v[84:85]
	v_pk_add_f32 v[54:55], v[54:55], v[86:87]
	v_pk_add_f32 v[56:57], v[56:57], v[88:89]
	v_pk_add_f32 v[58:59], v[58:59], v[90:91]
	v_pk_add_f32 v[60:61], v[60:61], v[92:93]
	v_pk_add_f32 v[62:63], v[62:63], v[94:95]
	v_pk_mul_f32 v[76:77], v[48:49], v[48:49]
	v_pk_fma_f32 v[76:77], v[50:51], v[50:51], v[76:77]
	v_pk_fma_f32 v[76:77], v[52:53], v[52:53], v[76:77]
	v_pk_fma_f32 v[76:77], v[54:55], v[54:55], v[76:77]
	v_pk_fma_f32 v[76:77], v[56:57], v[56:57], v[76:77]
	v_pk_fma_f32 v[76:77], v[58:59], v[58:59], v[76:77]
	v_pk_fma_f32 v[76:77], v[60:61], v[60:61], v[76:77]
	v_pk_fma_f32 v[76:77], v[62:63], v[62:63], v[76:77]
	ds_read2st64_b32 v[80:81], v67 offset0:16 offset1:17
	ds_read2st64_b32 v[82:83], v67 offset0:18 offset1:19
	ds_read2st64_b32 v[84:85], v67 offset0:20 offset1:21
	ds_read2st64_b32 v[86:87], v67 offset0:22 offset1:23
	ds_read2st64_b32 v[88:89], v67 offset0:24 offset1:25
	ds_read2st64_b32 v[90:91], v67 offset0:26 offset1:27
	ds_read2st64_b32 v[92:93], v67 offset0:28 offset1:29
	ds_read2st64_b32 v[94:95], v67 offset0:30 offset1:31
	s_waitcnt lgkmcnt(0)
	v_pk_add_f32 v[32:33], v[32:33], v[80:81]
	v_pk_add_f32 v[34:35], v[34:35], v[82:83]
	v_pk_add_f32 v[36:37], v[36:37], v[84:85]
	v_pk_add_f32 v[38:39], v[38:39], v[86:87]
	v_pk_add_f32 v[40:41], v[40:41], v[88:89]
	v_pk_add_f32 v[42:43], v[42:43], v[90:91]
	v_pk_add_f32 v[44:45], v[44:45], v[92:93]
	v_pk_add_f32 v[46:47], v[46:47], v[94:95]
	v_pk_fma_f32 v[76:77], v[32:33], v[32:33], v[76:77]
	v_pk_fma_f32 v[76:77], v[34:35], v[34:35], v[76:77]
	v_pk_fma_f32 v[76:77], v[36:37], v[36:37], v[76:77]
	v_pk_fma_f32 v[76:77], v[38:39], v[38:39], v[76:77]
	v_pk_fma_f32 v[76:77], v[40:41], v[40:41], v[76:77]
	v_pk_fma_f32 v[76:77], v[42:43], v[42:43], v[76:77]
	v_pk_fma_f32 v[76:77], v[44:45], v[44:45], v[76:77]
	v_pk_fma_f32 v[76:77], v[46:47], v[46:47], v[76:77]
	v_add_f32_e32 v69, v76, v77
	ds_bpermute_b32 v72, v244, v69
	s_waitcnt lgkmcnt(0)
	v_add_f32_e32 v69, v69, v72
	ds_write_b32 v68, v69
	s_waitcnt lgkmcnt(0)
	s_barrier
	ds_read_b32 v72, v68 offset:256
	v_mov_b32_e32 v74, 0x358637bd
	v_sub_f32_e64 v75, 1.0, s2
	s_waitcnt lgkmcnt(0)
	v_add_f32_e32 v69, v69, v72
	v_fmamk_f32 v69, v69, 0x3c000000, v74
	v_rsq_f32_e32 v69, v69
	s_nop 0
	v_mul_f32_e32 v70, v75, v69
	v_lshl_add_u32 v72, v188, 4, 0
	v_add_u32_e32 v72, 0x26b30, v72
	s_waitcnt vmcnt(0)
	s_mov_b32 s16, 0xbfb8aa3b
	s_mov_b32 s18, 1.0
	ds_read_b128 v[216:219], v72 offset:0
	v_lshlrev_b32_e32 v96, 16, v200
	v_and_b32_e32 v97, 0xffff0000, v200
	v_lshlrev_b32_e32 v98, 16, v201
	v_and_b32_e32 v99, 0xffff0000, v201
	v_pk_mul_f32 v[104:105], v[96:97], s[16:17] op_sel_hi:[1,0]
	v_pk_mul_f32 v[106:107], v[98:99], s[16:17] op_sel_hi:[1,0]
	v_exp_f32_e32 v104, v104
	v_exp_f32_e32 v105, v105
	v_exp_f32_e32 v106, v106
	v_exp_f32_e32 v107, v107
	v_pk_add_f32 v[104:105], v[104:105], s[18:19] op_sel_hi:[1,0]
	v_pk_add_f32 v[106:107], v[106:107], s[18:19] op_sel_hi:[1,0]
	v_div_scale_f32 v108, s[0:1], v104, v104, v96
	v_div_scale_f32 v109, s[0:1], v105, v105, v97
	v_div_scale_f32 v110, s[0:1], v106, v106, v98
	v_div_scale_f32 v111, s[0:1], v107, v107, v99
	v_rcp_f32_e32 v112, v108
	v_rcp_f32_e32 v113, v109
	v_rcp_f32_e32 v114, v110
	v_rcp_f32_e32 v115, v111
	v_pk_fma_f32 v[100:101], v[108:109], v[112:113], s[18:19] op_sel_hi:[1,1,0] neg_lo:[1,0,0] neg_hi:[1,0,0]
	v_pk_fma_f32 v[102:103], v[110:111], v[114:115], s[18:19] op_sel_hi:[1,1,0] neg_lo:[1,0,0] neg_hi:[1,0,0]
	v_pk_fma_f32 v[112:113], v[100:101], v[112:113], v[112:113]
	v_pk_fma_f32 v[114:115], v[102:103], v[114:115], v[114:115]
	v_div_scale_f32 v116, s[2:3], v96, v104, v96
	v_div_scale_f32 v117, vcc, v97, v105, v97
	v_pk_mul_f32 v[100:101], v[116:117], v[112:113]
	v_pk_fma_f32 v[120:121], v[108:109], v[100:101], v[116:117] neg_lo:[1,0,0] neg_hi:[1,0,0]
	v_pk_fma_f32 v[100:101], v[120:121], v[112:113], v[100:101]
	v_pk_fma_f32 v[120:121], v[108:109], v[100:101], v[116:117] neg_lo:[1,0,0] neg_hi:[1,0,0]
	v_div_fmas_f32 v121, v121, v113, v101
	v_div_fixup_f32 v101, v121, v105, v97
	s_mov_b64 vcc, s[2:3]
	s_nop 1
	v_div_fmas_f32 v120, v120, v112, v100
	v_div_fixup_f32 v100, v120, v104, v96
	v_div_scale_f32 v118, s[2:3], v98, v106, v98
	v_div_scale_f32 v119, vcc, v99, v107, v99
	v_pk_mul_f32 v[102:103], v[118:119], v[114:115]
	v_pk_fma_f32 v[122:123], v[110:111], v[102:103], v[118:119] neg_lo:[1,0,0] neg_hi:[1,0,0]
	v_pk_fma_f32 v[102:103], v[122:123], v[114:115], v[102:103]
	v_pk_fma_f32 v[122:123], v[110:111], v[102:103], v[118:119] neg_lo:[1,0,0] neg_hi:[1,0,0]
	v_div_fmas_f32 v123, v123, v115, v103
	v_div_fixup_f32 v103, v123, v107, v99
	s_mov_b64 vcc, s[2:3]
	s_nop 1
	v_div_fmas_f32 v122, v122, v114, v102
	v_div_fixup_f32 v102, v122, v106, v98
	s_waitcnt lgkmcnt(0)
; __device__ __forceinline__ float bflo(unsigned w) { return __uint_as_float(w << 16); }
; __device__ __forceinline__ float bfhi(unsigned w) { return __uint_as_float(w & 0xffff0000u); }
; __device__ __forceinline__ float silu_f(float x) { return x / (1.0f + __expf(-x)); }
; __device__ void da_unit(char* lds, const Params& p, int layer, int unit) {
;     ...
;             for (int g = 0; g < 4; ++g) {
;                 const int d0 = 32 * k + 8 * g + 4 * h2;
;                 const f32x4 gg = *(const f32x4*)(sg + d0);
;                 const u32x2 gw = gwv[k * 4 + g];
;                 const float o0 = O[k][4 * g + 0] * rstd * gg[0] * silu_f(bflo(gw.x));
;                 const float o1 = O[k][4 * g + 1] * rstd * gg[1] * silu_f(bfhi(gw.x));
;                 const float o2 = O[k][4 * g + 2] * rstd * gg[2] * silu_f(bflo(gw.y));
;                 const float o3 = O[k][4 * g + 3] * rstd * gg[3] * silu_f(bfhi(gw.y));
;                 u32x2 w; w.x = cvt_pk_bf16(o0, o1); w.y = cvt_pk_bf16(o2, o3);
;                 *(u32x2*)(p.o + tokq * 1024 + h * 128 + d0) = w;
;             }
	v_pk_mul_f32 v[48:49], v[48:49], v[70:71] op_sel_hi:[1,0]
	v_pk_mul_f32 v[48:49], v[48:49], v[216:217]
	v_pk_mul_f32 v[48:49], v[48:49], v[100:101]
	v_pk_mul_f32 v[50:51], v[50:51], v[70:71] op_sel_hi:[1,0]
	v_pk_mul_f32 v[50:51], v[50:51], v[218:219]
	v_pk_mul_f32 v[50:51], v[50:51], v[102:103]
	v_cvt_pk_bf16_f32 v96, v48, v49
	v_cvt_pk_bf16_f32 v97, v50, v51
	global_store_dwordx2 v[78:79], v[96:97], off offset:0
	ds_read_b128 v[216:219], v72 offset:32
	v_lshlrev_b32_e32 v96, 16, v202
	v_and_b32_e32 v97, 0xffff0000, v202
	v_lshlrev_b32_e32 v98, 16, v203
	v_and_b32_e32 v99, 0xffff0000, v203
	v_pk_mul_f32 v[104:105], v[96:97], s[16:17] op_sel_hi:[1,0]
	v_pk_mul_f32 v[106:107], v[98:99], s[16:17] op_sel_hi:[1,0]
	v_exp_f32_e32 v104, v104
	v_exp_f32_e32 v105, v105
	v_exp_f32_e32 v106, v106
	v_exp_f32_e32 v107, v107
	v_pk_add_f32 v[104:105], v[104:105], s[18:19] op_sel_hi:[1,0]
	v_pk_add_f32 v[106:107], v[106:107], s[18:19] op_sel_hi:[1,0]
	v_div_scale_f32 v108, s[0:1], v104, v104, v96
	v_div_scale_f32 v109, s[0:1], v105, v105, v97
	v_div_scale_f32 v110, s[0:1], v106, v106, v98
	v_div_scale_f32 v111, s[0:1], v107, v107, v99
	v_rcp_f32_e32 v112, v108
	v_rcp_f32_e32 v113, v109
	v_rcp_f32_e32 v114, v110
	v_rcp_f32_e32 v115, v111
	v_pk_fma_f32 v[100:101], v[108:109], v[112:113], s[18:19] op_sel_hi:[1,1,0] neg_lo:[1,0,0] neg_hi:[1,0,0]
	v_pk_fma_f32 v[102:103], v[110:111], v[114:115], s[18:19] op_sel_hi:[1,1,0] neg_lo:[1,0,0] neg_hi:[1,0,0]
	v_pk_fma_f32 v[112:113], v[100:101], v[112:113], v[112:113]
	v_pk_fma_f32 v[114:115], v[102:103], v[114:115], v[114:115]
	v_div_scale_f32 v116, s[2:3], v96, v104, v96
	v_div_scale_f32 v117, vcc, v97, v105, v97
	v_pk_mul_f32 v[100:101], v[116:117], v[112:113]
	v_pk_fma_f32 v[120:121], v[108:109], v[100:101], v[116:117] neg_lo:[1,0,0] neg_hi:[1,0,0]
	v_pk_fma_f32 v[100:101], v[120:121], v[112:113], v[100:101]
	v_pk_fma_f32 v[120:121], v[108:109], v[100:101], v[116:117] neg_lo:[1,0,0] neg_hi:[1,0,0]
	v_div_fmas_f32 v121, v121, v113, v101
	v_div_fixup_f32 v101, v121, v105, v97
	s_mov_b64 vcc, s[2:3]
	s_nop 1
	v_div_fmas_f32 v120, v120, v112, v100
	v_div_fixup_f32 v100, v120, v104, v96
	v_div_scale_f32 v118, s[2:3], v98, v106, v98
	v_div_scale_f32 v119, vcc, v99, v107, v99
	v_pk_mul_f32 v[102:103], v[118:119], v[114:115]
	v_pk_fma_f32 v[122:123], v[110:111], v[102:103], v[118:119] neg_lo:[1,0,0] neg_hi:[1,0,0]
	v_pk_fma_f32 v[102:103], v[122:123], v[114:115], v[102:103]
	v_pk_fma_f32 v[122:123], v[110:111], v[102:103], v[118:119] neg_lo:[1,0,0] neg_hi:[1,0,0]
	v_div_fmas_f32 v123, v123, v115, v103
	v_div_fixup_f32 v103, v123, v107, v99
	s_mov_b64 vcc, s[2:3]
	s_nop 1
	v_div_fmas_f32 v122, v122, v114, v102
	v_div_fixup_f32 v102, v122, v106, v98
	s_waitcnt lgkmcnt(0)
	v_pk_mul_f32 v[52:53], v[52:53], v[70:71] op_sel_hi:[1,0]
	v_pk_mul_f32 v[52:53], v[52:53], v[216:217]
	v_pk_mul_f32 v[52:53], v[52:53], v[100:101]
	v_pk_mul_f32 v[54:55], v[54:55], v[70:71] op_sel_hi:[1,0]
	v_pk_mul_f32 v[54:55], v[54:55], v[218:219]
	v_pk_mul_f32 v[54:55], v[54:55], v[102:103]
	v_cvt_pk_bf16_f32 v96, v52, v53
	v_cvt_pk_bf16_f32 v97, v54, v55
	global_store_dwordx2 v[78:79], v[96:97], off offset:16
	ds_read_b128 v[216:219], v72 offset:64
	v_lshlrev_b32_e32 v96, 16, v204
	v_and_b32_e32 v97, 0xffff0000, v204
	v_lshlrev_b32_e32 v98, 16, v205
	v_and_b32_e32 v99, 0xffff0000, v205
	v_pk_mul_f32 v[104:105], v[96:97], s[16:17] op_sel_hi:[1,0]
	v_pk_mul_f32 v[106:107], v[98:99], s[16:17] op_sel_hi:[1,0]
	v_exp_f32_e32 v104, v104
	v_exp_f32_e32 v105, v105
	v_exp_f32_e32 v106, v106
	v_exp_f32_e32 v107, v107
	v_pk_add_f32 v[104:105], v[104:105], s[18:19] op_sel_hi:[1,0]
	v_pk_add_f32 v[106:107], v[106:107], s[18:19] op_sel_hi:[1,0]
	v_div_scale_f32 v108, s[0:1], v104, v104, v96
	v_div_scale_f32 v109, s[0:1], v105, v105, v97
	v_div_scale_f32 v110, s[0:1], v106, v106, v98
	v_div_scale_f32 v111, s[0:1], v107, v107, v99
	v_rcp_f32_e32 v112, v108
	v_rcp_f32_e32 v113, v109
	v_rcp_f32_e32 v114, v110
	v_rcp_f32_e32 v115, v111
	v_pk_fma_f32 v[100:101], v[108:109], v[112:113], s[18:19] op_sel_hi:[1,1,0] neg_lo:[1,0,0] neg_hi:[1,0,0]
	v_pk_fma_f32 v[102:103], v[110:111], v[114:115], s[18:19] op_sel_hi:[1,1,0] neg_lo:[1,0,0] neg_hi:[1,0,0]
	v_pk_fma_f32 v[112:113], v[100:101], v[112:113], v[112:113]
	v_pk_fma_f32 v[114:115], v[102:103], v[114:115], v[114:115]
	v_div_scale_f32 v116, s[2:3], v96, v104, v96
	v_div_scale_f32 v117, vcc, v97, v105, v97
	v_pk_mul_f32 v[100:101], v[116:117], v[112:113]
	v_pk_fma_f32 v[120:121], v[108:109], v[100:101], v[116:117] neg_lo:[1,0,0] neg_hi:[1,0,0]
	v_pk_fma_f32 v[100:101], v[120:121], v[112:113], v[100:101]
	v_pk_fma_f32 v[120:121], v[108:109], v[100:101], v[116:117] neg_lo:[1,0,0] neg_hi:[1,0,0]
	v_div_fmas_f32 v121, v121, v113, v101
	v_div_fixup_f32 v101, v121, v105, v97
	s_mov_b64 vcc, s[2:3]
	s_nop 1
	v_div_fmas_f32 v120, v120, v112, v100
	v_div_fixup_f32 v100, v120, v104, v96
	v_div_scale_f32 v118, s[2:3], v98, v106, v98
	v_div_scale_f32 v119, vcc, v99, v107, v99
	v_pk_mul_f32 v[102:103], v[118:119], v[114:115]
	v_pk_fma_f32 v[122:123], v[110:111], v[102:103], v[118:119] neg_lo:[1,0,0] neg_hi:[1,0,0]
	v_pk_fma_f32 v[102:103], v[122:123], v[114:115], v[102:103]
	v_pk_fma_f32 v[122:123], v[110:111], v[102:103], v[118:119] neg_lo:[1,0,0] neg_hi:[1,0,0]
	v_div_fmas_f32 v123, v123, v115, v103
	v_div_fixup_f32 v103, v123, v107, v99
	s_mov_b64 vcc, s[2:3]
	s_nop 1
	v_div_fmas_f32 v122, v122, v114, v102
	v_div_fixup_f32 v102, v122, v106, v98
	s_waitcnt lgkmcnt(0)
; __device__ __forceinline__ float bflo(unsigned w) { return __uint_as_float(w << 16); }
; __device__ __forceinline__ float bfhi(unsigned w) { return __uint_as_float(w & 0xffff0000u); }
; __device__ __forceinline__ float silu_f(float x) { return x / (1.0f + __expf(-x)); }
; __device__ void da_unit(char* lds, const Params& p, int layer, int unit) {
;     ...
;             for (int g = 0; g < 4; ++g) {
;                 const int d0 = 32 * k + 8 * g + 4 * h2;
;                 const f32x4 gg = *(const f32x4*)(sg + d0);
;                 const u32x2 gw = gwv[k * 4 + g];
;                 const float o0 = O[k][4 * g + 0] * rstd * gg[0] * silu_f(bflo(gw.x));
;                 const float o1 = O[k][4 * g + 1] * rstd * gg[1] * silu_f(bfhi(gw.x));
;                 const float o2 = O[k][4 * g + 2] * rstd * gg[2] * silu_f(bflo(gw.y));
;                 const float o3 = O[k][4 * g + 3] * rstd * gg[3] * silu_f(bfhi(gw.y));
;                 u32x2 w; w.x = cvt_pk_bf16(o0, o1); w.y = cvt_pk_bf16(o2, o3);
;                 *(u32x2*)(p.o + tokq * 1024 + h * 128 + d0) = w;
;             }
	v_pk_mul_f32 v[56:57], v[56:57], v[70:71] op_sel_hi:[1,0]
	v_pk_mul_f32 v[56:57], v[56:57], v[216:217]
	v_pk_mul_f32 v[56:57], v[56:57], v[100:101]
	v_pk_mul_f32 v[58:59], v[58:59], v[70:71] op_sel_hi:[1,0]
	v_pk_mul_f32 v[58:59], v[58:59], v[218:219]
	v_pk_mul_f32 v[58:59], v[58:59], v[102:103]
	v_cvt_pk_bf16_f32 v96, v56, v57
	v_cvt_pk_bf16_f32 v97, v58, v59
	global_store_dwordx2 v[78:79], v[96:97], off offset:32
	ds_read_b128 v[216:219], v72 offset:96
	v_lshlrev_b32_e32 v96, 16, v206
	v_and_b32_e32 v97, 0xffff0000, v206
	v_lshlrev_b32_e32 v98, 16, v207
	v_and_b32_e32 v99, 0xffff0000, v207
	v_pk_mul_f32 v[104:105], v[96:97], s[16:17] op_sel_hi:[1,0]
	v_pk_mul_f32 v[106:107], v[98:99], s[16:17] op_sel_hi:[1,0]
	v_exp_f32_e32 v104, v104
	v_exp_f32_e32 v105, v105
	v_exp_f32_e32 v106, v106
	v_exp_f32_e32 v107, v107
	v_pk_add_f32 v[104:105], v[104:105], s[18:19] op_sel_hi:[1,0]
	v_pk_add_f32 v[106:107], v[106:107], s[18:19] op_sel_hi:[1,0]
	v_div_scale_f32 v108, s[0:1], v104, v104, v96
	v_div_scale_f32 v109, s[0:1], v105, v105, v97
	v_div_scale_f32 v110, s[0:1], v106, v106, v98
	v_div_scale_f32 v111, s[0:1], v107, v107, v99
	v_rcp_f32_e32 v112, v108
	v_rcp_f32_e32 v113, v109
	v_rcp_f32_e32 v114, v110
	v_rcp_f32_e32 v115, v111
	v_pk_fma_f32 v[100:101], v[108:109], v[112:113], s[18:19] op_sel_hi:[1,1,0] neg_lo:[1,0,0] neg_hi:[1,0,0]
	v_pk_fma_f32 v[102:103], v[110:111], v[114:115], s[18:19] op_sel_hi:[1,1,0] neg_lo:[1,0,0] neg_hi:[1,0,0]
	v_pk_fma_f32 v[112:113], v[100:101], v[112:113], v[112:113]
	v_pk_fma_f32 v[114:115], v[102:103], v[114:115], v[114:115]
	v_div_scale_f32 v116, s[2:3], v96, v104, v96
	v_div_scale_f32 v117, vcc, v97, v105, v97
	v_pk_mul_f32 v[100:101], v[116:117], v[112:113]
	v_pk_fma_f32 v[120:121], v[108:109], v[100:101], v[116:117] neg_lo:[1,0,0] neg_hi:[1,0,0]
	v_pk_fma_f32 v[100:101], v[120:121], v[112:113], v[100:101]
	v_pk_fma_f32 v[120:121], v[108:109], v[100:101], v[116:117] neg_lo:[1,0,0] neg_hi:[1,0,0]
	v_div_fmas_f32 v121, v121, v113, v101
	v_div_fixup_f32 v101, v121, v105, v97
	s_mov_b64 vcc, s[2:3]
	s_nop 1
	v_div_fmas_f32 v120, v120, v112, v100
	v_div_fixup_f32 v100, v120, v104, v96
	v_div_scale_f32 v118, s[2:3], v98, v106, v98
	v_div_scale_f32 v119, vcc, v99, v107, v99
	v_pk_mul_f32 v[102:103], v[118:119], v[114:115]
	v_pk_fma_f32 v[122:123], v[110:111], v[102:103], v[118:119] neg_lo:[1,0,0] neg_hi:[1,0,0]
	v_pk_fma_f32 v[102:103], v[122:123], v[114:115], v[102:103]
	v_pk_fma_f32 v[122:123], v[110:111], v[102:103], v[118:119] neg_lo:[1,0,0] neg_hi:[1,0,0]
	v_div_fmas_f32 v123, v123, v115, v103
	v_div_fixup_f32 v103, v123, v107, v99
	s_mov_b64 vcc, s[2:3]
	s_nop 1
	v_div_fmas_f32 v122, v122, v114, v102
	v_div_fixup_f32 v102, v122, v106, v98
	s_waitcnt lgkmcnt(0)
	v_pk_mul_f32 v[60:61], v[60:61], v[70:71] op_sel_hi:[1,0]
	v_pk_mul_f32 v[60:61], v[60:61], v[216:217]
	v_pk_mul_f32 v[60:61], v[60:61], v[100:101]
	v_pk_mul_f32 v[62:63], v[62:63], v[70:71] op_sel_hi:[1,0]
	v_pk_mul_f32 v[62:63], v[62:63], v[218:219]
	v_pk_mul_f32 v[62:63], v[62:63], v[102:103]
	v_cvt_pk_bf16_f32 v96, v60, v61
	v_cvt_pk_bf16_f32 v97, v62, v63
	global_store_dwordx2 v[78:79], v[96:97], off offset:48
	ds_read_b128 v[216:219], v72 offset:128
	v_lshlrev_b32_e32 v96, 16, v208
	v_and_b32_e32 v97, 0xffff0000, v208
	v_lshlrev_b32_e32 v98, 16, v209
	v_and_b32_e32 v99, 0xffff0000, v209
	v_pk_mul_f32 v[104:105], v[96:97], s[16:17] op_sel_hi:[1,0]
	v_pk_mul_f32 v[106:107], v[98:99], s[16:17] op_sel_hi:[1,0]
	v_exp_f32_e32 v104, v104
	v_exp_f32_e32 v105, v105
	v_exp_f32_e32 v106, v106
	v_exp_f32_e32 v107, v107
	v_pk_add_f32 v[104:105], v[104:105], s[18:19] op_sel_hi:[1,0]
	v_pk_add_f32 v[106:107], v[106:107], s[18:19] op_sel_hi:[1,0]
	v_div_scale_f32 v108, s[0:1], v104, v104, v96
	v_div_scale_f32 v109, s[0:1], v105, v105, v97
	v_div_scale_f32 v110, s[0:1], v106, v106, v98
	v_div_scale_f32 v111, s[0:1], v107, v107, v99
	v_rcp_f32_e32 v112, v108
	v_rcp_f32_e32 v113, v109
	v_rcp_f32_e32 v114, v110
	v_rcp_f32_e32 v115, v111
	v_pk_fma_f32 v[100:101], v[108:109], v[112:113], s[18:19] op_sel_hi:[1,1,0] neg_lo:[1,0,0] neg_hi:[1,0,0]
	v_pk_fma_f32 v[102:103], v[110:111], v[114:115], s[18:19] op_sel_hi:[1,1,0] neg_lo:[1,0,0] neg_hi:[1,0,0]
	v_pk_fma_f32 v[112:113], v[100:101], v[112:113], v[112:113]
	v_pk_fma_f32 v[114:115], v[102:103], v[114:115], v[114:115]
	v_div_scale_f32 v116, s[2:3], v96, v104, v96
	v_div_scale_f32 v117, vcc, v97, v105, v97
	v_pk_mul_f32 v[100:101], v[116:117], v[112:113]
	v_pk_fma_f32 v[120:121], v[108:109], v[100:101], v[116:117] neg_lo:[1,0,0] neg_hi:[1,0,0]
	v_pk_fma_f32 v[100:101], v[120:121], v[112:113], v[100:101]
	v_pk_fma_f32 v[120:121], v[108:109], v[100:101], v[116:117] neg_lo:[1,0,0] neg_hi:[1,0,0]
	v_div_fmas_f32 v121, v121, v113, v101
	v_div_fixup_f32 v101, v121, v105, v97
	s_mov_b64 vcc, s[2:3]
	s_nop 1
	v_div_fmas_f32 v120, v120, v112, v100
	v_div_fixup_f32 v100, v120, v104, v96
	v_div_scale_f32 v118, s[2:3], v98, v106, v98
	v_div_scale_f32 v119, vcc, v99, v107, v99
	v_pk_mul_f32 v[102:103], v[118:119], v[114:115]
	v_pk_fma_f32 v[122:123], v[110:111], v[102:103], v[118:119] neg_lo:[1,0,0] neg_hi:[1,0,0]
	v_pk_fma_f32 v[102:103], v[122:123], v[114:115], v[102:103]
	v_pk_fma_f32 v[122:123], v[110:111], v[102:103], v[118:119] neg_lo:[1,0,0] neg_hi:[1,0,0]
	v_div_fmas_f32 v123, v123, v115, v103
	v_div_fixup_f32 v103, v123, v107, v99
	s_mov_b64 vcc, s[2:3]
	s_nop 1
	v_div_fmas_f32 v122, v122, v114, v102
	v_div_fixup_f32 v102, v122, v106, v98
	s_waitcnt lgkmcnt(0)
; __device__ __forceinline__ float bflo(unsigned w) { return __uint_as_float(w << 16); }
; __device__ __forceinline__ float bfhi(unsigned w) { return __uint_as_float(w & 0xffff0000u); }
; __device__ __forceinline__ float silu_f(float x) { return x / (1.0f + __expf(-x)); }
; __device__ void da_unit(char* lds, const Params& p, int layer, int unit) {
;     ...
;             for (int g = 0; g < 4; ++g) {
;                 const int d0 = 32 * k + 8 * g + 4 * h2;
;                 const f32x4 gg = *(const f32x4*)(sg + d0);
;                 const u32x2 gw = gwv[k * 4 + g];
;                 const float o0 = O[k][4 * g + 0] * rstd * gg[0] * silu_f(bflo(gw.x));
;                 const float o1 = O[k][4 * g + 1] * rstd * gg[1] * silu_f(bfhi(gw.x));
;                 const float o2 = O[k][4 * g + 2] * rstd * gg[2] * silu_f(bflo(gw.y));
;                 const float o3 = O[k][4 * g + 3] * rstd * gg[3] * silu_f(bfhi(gw.y));
;                 u32x2 w; w.x = cvt_pk_bf16(o0, o1); w.y = cvt_pk_bf16(o2, o3);
;                 *(u32x2*)(p.o + tokq * 1024 + h * 128 + d0) = w;
;             }
	v_pk_mul_f32 v[32:33], v[32:33], v[70:71] op_sel_hi:[1,0]
	v_pk_mul_f32 v[32:33], v[32:33], v[216:217]
	v_pk_mul_f32 v[32:33], v[32:33], v[100:101]
	v_pk_mul_f32 v[34:35], v[34:35], v[70:71] op_sel_hi:[1,0]
	v_pk_mul_f32 v[34:35], v[34:35], v[218:219]
	v_pk_mul_f32 v[34:35], v[34:35], v[102:103]
	v_cvt_pk_bf16_f32 v96, v32, v33
	v_cvt_pk_bf16_f32 v97, v34, v35
	global_store_dwordx2 v[78:79], v[96:97], off offset:64
	ds_read_b128 v[216:219], v72 offset:160
	v_lshlrev_b32_e32 v96, 16, v210
	v_and_b32_e32 v97, 0xffff0000, v210
	v_lshlrev_b32_e32 v98, 16, v211
	v_and_b32_e32 v99, 0xffff0000, v211
	v_pk_mul_f32 v[104:105], v[96:97], s[16:17] op_sel_hi:[1,0]
	v_pk_mul_f32 v[106:107], v[98:99], s[16:17] op_sel_hi:[1,0]
	v_exp_f32_e32 v104, v104
	v_exp_f32_e32 v105, v105
	v_exp_f32_e32 v106, v106
	v_exp_f32_e32 v107, v107
	v_pk_add_f32 v[104:105], v[104:105], s[18:19] op_sel_hi:[1,0]
	v_pk_add_f32 v[106:107], v[106:107], s[18:19] op_sel_hi:[1,0]
	v_div_scale_f32 v108, s[0:1], v104, v104, v96
	v_div_scale_f32 v109, s[0:1], v105, v105, v97
	v_div_scale_f32 v110, s[0:1], v106, v106, v98
	v_div_scale_f32 v111, s[0:1], v107, v107, v99
	v_rcp_f32_e32 v112, v108
	v_rcp_f32_e32 v113, v109
	v_rcp_f32_e32 v114, v110
	v_rcp_f32_e32 v115, v111
	v_pk_fma_f32 v[100:101], v[108:109], v[112:113], s[18:19] op_sel_hi:[1,1,0] neg_lo:[1,0,0] neg_hi:[1,0,0]
	v_pk_fma_f32 v[102:103], v[110:111], v[114:115], s[18:19] op_sel_hi:[1,1,0] neg_lo:[1,0,0] neg_hi:[1,0,0]
	v_pk_fma_f32 v[112:113], v[100:101], v[112:113], v[112:113]
	v_pk_fma_f32 v[114:115], v[102:103], v[114:115], v[114:115]
	v_div_scale_f32 v116, s[2:3], v96, v104, v96
	v_div_scale_f32 v117, vcc, v97, v105, v97
	v_pk_mul_f32 v[100:101], v[116:117], v[112:113]
	v_pk_fma_f32 v[120:121], v[108:109], v[100:101], v[116:117] neg_lo:[1,0,0] neg_hi:[1,0,0]
	v_pk_fma_f32 v[100:101], v[120:121], v[112:113], v[100:101]
	v_pk_fma_f32 v[120:121], v[108:109], v[100:101], v[116:117] neg_lo:[1,0,0] neg_hi:[1,0,0]
	v_div_fmas_f32 v121, v121, v113, v101
	v_div_fixup_f32 v101, v121, v105, v97
	s_mov_b64 vcc, s[2:3]
	s_nop 1
	v_div_fmas_f32 v120, v120, v112, v100
	v_div_fixup_f32 v100, v120, v104, v96
	v_div_scale_f32 v118, s[2:3], v98, v106, v98
	v_div_scale_f32 v119, vcc, v99, v107, v99
	v_pk_mul_f32 v[102:103], v[118:119], v[114:115]
	v_pk_fma_f32 v[122:123], v[110:111], v[102:103], v[118:119] neg_lo:[1,0,0] neg_hi:[1,0,0]
	v_pk_fma_f32 v[102:103], v[122:123], v[114:115], v[102:103]
	v_pk_fma_f32 v[122:123], v[110:111], v[102:103], v[118:119] neg_lo:[1,0,0] neg_hi:[1,0,0]
	v_div_fmas_f32 v123, v123, v115, v103
	v_div_fixup_f32 v103, v123, v107, v99
	s_mov_b64 vcc, s[2:3]
	s_nop 1
	v_div_fmas_f32 v122, v122, v114, v102
	v_div_fixup_f32 v102, v122, v106, v98
	s_waitcnt lgkmcnt(0)
	v_pk_mul_f32 v[36:37], v[36:37], v[70:71] op_sel_hi:[1,0]
	v_pk_mul_f32 v[36:37], v[36:37], v[216:217]
	v_pk_mul_f32 v[36:37], v[36:37], v[100:101]
	v_pk_mul_f32 v[38:39], v[38:39], v[70:71] op_sel_hi:[1,0]
	v_pk_mul_f32 v[38:39], v[38:39], v[218:219]
	v_pk_mul_f32 v[38:39], v[38:39], v[102:103]
	v_cvt_pk_bf16_f32 v96, v36, v37
	v_cvt_pk_bf16_f32 v97, v38, v39
	global_store_dwordx2 v[78:79], v[96:97], off offset:80
	ds_read_b128 v[216:219], v72 offset:192
	v_lshlrev_b32_e32 v96, 16, v212
	v_and_b32_e32 v97, 0xffff0000, v212
	v_lshlrev_b32_e32 v98, 16, v213
	v_and_b32_e32 v99, 0xffff0000, v213
	v_pk_mul_f32 v[104:105], v[96:97], s[16:17] op_sel_hi:[1,0]
	v_pk_mul_f32 v[106:107], v[98:99], s[16:17] op_sel_hi:[1,0]
	v_exp_f32_e32 v104, v104
	v_exp_f32_e32 v105, v105
	v_exp_f32_e32 v106, v106
	v_exp_f32_e32 v107, v107
	v_pk_add_f32 v[104:105], v[104:105], s[18:19] op_sel_hi:[1,0]
	v_pk_add_f32 v[106:107], v[106:107], s[18:19] op_sel_hi:[1,0]
	v_div_scale_f32 v108, s[0:1], v104, v104, v96
	v_div_scale_f32 v109, s[0:1], v105, v105, v97
	v_div_scale_f32 v110, s[0:1], v106, v106, v98
	v_div_scale_f32 v111, s[0:1], v107, v107, v99
	v_rcp_f32_e32 v112, v108
	v_rcp_f32_e32 v113, v109
	v_rcp_f32_e32 v114, v110
	v_rcp_f32_e32 v115, v111
	v_pk_fma_f32 v[100:101], v[108:109], v[112:113], s[18:19] op_sel_hi:[1,1,0] neg_lo:[1,0,0] neg_hi:[1,0,0]
	v_pk_fma_f32 v[102:103], v[110:111], v[114:115], s[18:19] op_sel_hi:[1,1,0] neg_lo:[1,0,0] neg_hi:[1,0,0]
	v_pk_fma_f32 v[112:113], v[100:101], v[112:113], v[112:113]
	v_pk_fma_f32 v[114:115], v[102:103], v[114:115], v[114:115]
	v_div_scale_f32 v116, s[2:3], v96, v104, v96
	v_div_scale_f32 v117, vcc, v97, v105, v97
	v_pk_mul_f32 v[100:101], v[116:117], v[112:113]
	v_pk_fma_f32 v[120:121], v[108:109], v[100:101], v[116:117] neg_lo:[1,0,0] neg_hi:[1,0,0]
	v_pk_fma_f32 v[100:101], v[120:121], v[112:113], v[100:101]
	v_pk_fma_f32 v[120:121], v[108:109], v[100:101], v[116:117] neg_lo:[1,0,0] neg_hi:[1,0,0]
	v_div_fmas_f32 v121, v121, v113, v101
	v_div_fixup_f32 v101, v121, v105, v97
	s_mov_b64 vcc, s[2:3]
	s_nop 1
	v_div_fmas_f32 v120, v120, v112, v100
	v_div_fixup_f32 v100, v120, v104, v96
	v_div_scale_f32 v118, s[2:3], v98, v106, v98
	v_div_scale_f32 v119, vcc, v99, v107, v99
	v_pk_mul_f32 v[102:103], v[118:119], v[114:115]
	v_pk_fma_f32 v[122:123], v[110:111], v[102:103], v[118:119] neg_lo:[1,0,0] neg_hi:[1,0,0]
	v_pk_fma_f32 v[102:103], v[122:123], v[114:115], v[102:103]
	v_pk_fma_f32 v[122:123], v[110:111], v[102:103], v[118:119] neg_lo:[1,0,0] neg_hi:[1,0,0]
	v_div_fmas_f32 v123, v123, v115, v103
	v_div_fixup_f32 v103, v123, v107, v99
	s_mov_b64 vcc, s[2:3]
	s_nop 1
	v_div_fmas_f32 v122, v122, v114, v102
	v_div_fixup_f32 v102, v122, v106, v98
	s_waitcnt lgkmcnt(0)
; __device__ __forceinline__ float bflo(unsigned w) { return __uint_as_float(w << 16); }
; __device__ __forceinline__ float bfhi(unsigned w) { return __uint_as_float(w & 0xffff0000u); }
; __device__ __forceinline__ float silu_f(float x) { return x / (1.0f + __expf(-x)); }
; __device__ void da_unit(char* lds, const Params& p, int layer, int unit) {
;     ...
;             for (int g = 0; g < 4; ++g) {
;                 const int d0 = 32 * k + 8 * g + 4 * h2;
;                 const f32x4 gg = *(const f32x4*)(sg + d0);
;                 const u32x2 gw = gwv[k * 4 + g];
;                 const float o0 = O[k][4 * g + 0] * rstd * gg[0] * silu_f(bflo(gw.x));
;                 const float o1 = O[k][4 * g + 1] * rstd * gg[1] * silu_f(bfhi(gw.x));
;                 const float o2 = O[k][4 * g + 2] * rstd * gg[2] * silu_f(bflo(gw.y));
;                 const float o3 = O[k][4 * g + 3] * rstd * gg[3] * silu_f(bfhi(gw.y));
;                 u32x2 w; w.x = cvt_pk_bf16(o0, o1); w.y = cvt_pk_bf16(o2, o3);
;                 *(u32x2*)(p.o + tokq * 1024 + h * 128 + d0) = w;
;             }
	v_pk_mul_f32 v[40:41], v[40:41], v[70:71] op_sel_hi:[1,0]
	v_pk_mul_f32 v[40:41], v[40:41], v[216:217]
	v_pk_mul_f32 v[40:41], v[40:41], v[100:101]
	v_pk_mul_f32 v[42:43], v[42:43], v[70:71] op_sel_hi:[1,0]
	v_pk_mul_f32 v[42:43], v[42:43], v[218:219]
	v_pk_mul_f32 v[42:43], v[42:43], v[102:103]
	v_cvt_pk_bf16_f32 v96, v40, v41
	v_cvt_pk_bf16_f32 v97, v42, v43
	global_store_dwordx2 v[78:79], v[96:97], off offset:96
	ds_read_b128 v[216:219], v72 offset:224
	v_lshlrev_b32_e32 v96, 16, v214
	v_and_b32_e32 v97, 0xffff0000, v214
	v_lshlrev_b32_e32 v98, 16, v215
	v_and_b32_e32 v99, 0xffff0000, v215
	v_pk_mul_f32 v[104:105], v[96:97], s[16:17] op_sel_hi:[1,0]
	v_pk_mul_f32 v[106:107], v[98:99], s[16:17] op_sel_hi:[1,0]
	v_exp_f32_e32 v104, v104
	v_exp_f32_e32 v105, v105
	v_exp_f32_e32 v106, v106
	v_exp_f32_e32 v107, v107
	v_pk_add_f32 v[104:105], v[104:105], s[18:19] op_sel_hi:[1,0]
	v_pk_add_f32 v[106:107], v[106:107], s[18:19] op_sel_hi:[1,0]
	v_div_scale_f32 v108, s[0:1], v104, v104, v96
	v_div_scale_f32 v109, s[0:1], v105, v105, v97
	v_div_scale_f32 v110, s[0:1], v106, v106, v98
	v_div_scale_f32 v111, s[0:1], v107, v107, v99
	v_rcp_f32_e32 v112, v108
	v_rcp_f32_e32 v113, v109
	v_rcp_f32_e32 v114, v110
	v_rcp_f32_e32 v115, v111
	v_pk_fma_f32 v[100:101], v[108:109], v[112:113], s[18:19] op_sel_hi:[1,1,0] neg_lo:[1,0,0] neg_hi:[1,0,0]
	v_pk_fma_f32 v[102:103], v[110:111], v[114:115], s[18:19] op_sel_hi:[1,1,0] neg_lo:[1,0,0] neg_hi:[1,0,0]
	v_pk_fma_f32 v[112:113], v[100:101], v[112:113], v[112:113]
	v_pk_fma_f32 v[114:115], v[102:103], v[114:115], v[114:115]
	v_div_scale_f32 v116, s[2:3], v96, v104, v96
	v_div_scale_f32 v117, vcc, v97, v105, v97
	v_pk_mul_f32 v[100:101], v[116:117], v[112:113]
	v_pk_fma_f32 v[120:121], v[108:109], v[100:101], v[116:117] neg_lo:[1,0,0] neg_hi:[1,0,0]
	v_pk_fma_f32 v[100:101], v[120:121], v[112:113], v[100:101]
	v_pk_fma_f32 v[120:121], v[108:109], v[100:101], v[116:117] neg_lo:[1,0,0] neg_hi:[1,0,0]
	v_div_fmas_f32 v121, v121, v113, v101
	v_div_fixup_f32 v101, v121, v105, v97
	s_mov_b64 vcc, s[2:3]
	s_nop 1
	v_div_fmas_f32 v120, v120, v112, v100
	v_div_fixup_f32 v100, v120, v104, v96
	v_div_scale_f32 v118, s[2:3], v98, v106, v98
	v_div_scale_f32 v119, vcc, v99, v107, v99
	v_pk_mul_f32 v[102:103], v[118:119], v[114:115]
	v_pk_fma_f32 v[122:123], v[110:111], v[102:103], v[118:119] neg_lo:[1,0,0] neg_hi:[1,0,0]
	v_pk_fma_f32 v[102:103], v[122:123], v[114:115], v[102:103]
	v_pk_fma_f32 v[122:123], v[110:111], v[102:103], v[118:119] neg_lo:[1,0,0] neg_hi:[1,0,0]
	v_div_fmas_f32 v123, v123, v115, v103
	v_div_fixup_f32 v103, v123, v107, v99
	s_mov_b64 vcc, s[2:3]
	s_nop 1
	v_div_fmas_f32 v122, v122, v114, v102
	v_div_fixup_f32 v102, v122, v106, v98
	s_waitcnt lgkmcnt(0)
	v_pk_mul_f32 v[44:45], v[44:45], v[70:71] op_sel_hi:[1,0]
	v_pk_mul_f32 v[44:45], v[44:45], v[216:217]
	v_pk_mul_f32 v[44:45], v[44:45], v[100:101]
	v_pk_mul_f32 v[46:47], v[46:47], v[70:71] op_sel_hi:[1,0]
	v_pk_mul_f32 v[46:47], v[46:47], v[218:219]
	v_pk_mul_f32 v[46:47], v[46:47], v[102:103]
	v_cvt_pk_bf16_f32 v96, v44, v45
	v_cvt_pk_bf16_f32 v97, v46, v47
	global_store_dwordx2 v[78:79], v[96:97], off offset:112
	s_branch .LBB0_450
